# mLSTM unit: ALPHA[e1] (consumed after the block-state phase) requested at the top of the unit with the Q fragments
# speedup vs baseline: 1.0006x; 1.0006x over previous
; #define LAS __attribute__((address_space(3)))
; DI f32x16 zero16() { f32x16 z; for (int i = 0; i < 16; ++i) z[i] = 0.f; return z; }
; DI void mlstm_unit(const Args& a, LAS unsigned char* lds, int b, int h, int J) {
;     ...
;     const int tid = tid_, lane = tid & 63, wave = __builtin_amdgcn_readfirstlane(tid >> 6), r = lane & 31, h2 = lane >> 5;
;     const int seq = b * 4 + h, t = 256 * J + 32 * wave + r; const size_t row = (size_t)b * T + t;
;     const bf16_t* QB = (const bf16_t*)(ws + WS_QB); const bf16_t* KB = (const bf16_t*)(ws + WS_KB) + (size_t)b * T * 512 + h * 128; const bf16_t* VB = (const bf16_t*)(ws + WS_VB) + (size_t)b * T * 512 + h * 128;
;     const float* BETA = (const float*)(ws + WS_BETA) + seq * 2048; const float* ALPHA = (const float*)(ws + WS_ALPHA) + seq * 2048; const float* MTG = (const float*)(ws + WS_MT) + seq * 2048;
;     const LAS unsigned char* Ks = lds + A_KS; const LAS unsigned char* Vs = lds + A_VS; LAS float* BS = (LAS float*)(lds + M_BS); LAS float* KAP = (LAS float*)(lds + M_KAP); LAS float* NV = (LAS float*)(lds + M_NV);
;     bf16x8 qf[8];
; #pragma unroll
;     for (int ks = 0; ks < 8; ++ks) qf[ks] = *(const bf16x8*)(QB + row * 512 + h * 128 + 16 * ks + 8 * h2);
;     const float aln = ALPHA[t], al = aln * LOG2E, mt = MTG[t];
;     f32x16 O[4];
; #pragma unroll
;     for (int i = 0; i < 4; ++i) O[i] = zero16();
;     float den = 0.f;
;     __syncthreads();
;     if (J > 0) {
;         const int e1 = 256 * J - 1;
;         if (tid < J) { const int ep = 256 * tid + 255; const float Be1 = ALPHA[e1] + MTG[e1], Bep = ALPHA[ep] + MTG[ep];
;             KAP[tid] = __expf((Be1 - Bep) + ((const float*)(ws + WS_MU))[seq * 8 + tid] - MTG[e1]); }
;     ...
;     for (int i = 0; i < 2; ++i) { const int idx = tid + 512 * i, rw = 64 * kt0 + (idx >> 4), ch = idx & 15; kreg[i] = *(const u32x4*)(KB + (size_t)rw * 512 + ch * 8); vreg[i] = *(const u32x4*)(VB + (size_t)rw * 512 + ch * 8); }
.LBB0_2094:
	s_add_i32 s0, s20, 0xfffffda0
	s_ashr_i32 s1, s0, 31
	s_lshr_b32 s1, s1, 24
	s_add_i32 s1, s0, s1
	s_and_b32 s1, s1, 0xffffff00
	s_sub_i32 s49, s0, s1
	v_mov_b32_e32 v74, v0
	s_ashr_i32 s50, s49, 5
	s_sub_i32 s51, 7, s50
	v_readfirstlane_b32 s52, v74
	s_ashr_i32 s0, s52, 1
	s_lshl_b32 s18, s51, 8
	s_andn2_b32 s0, s0, 31
	v_and_b32_e32 v76, 31, v74
	s_add_i32 s0, s18, s0
	v_or_b32_e32 v156, s0, v76
	s_lshl_b32 s0, s49, 9
	s_and_b32 s10, s0, 0x3800
	v_ashrrev_i32_e32 v157, 31, v156
	v_lshl_add_u64 v[152:153], v[156:157], 0, s[10:11]
	s_lshl_b32 s0, s49, 7
	s_and_b32 s48, s0, 0x180
	v_lshlrev_b64 v[154:155], 10, v[152:153]
	v_bfe_u32 v75, v74, 5, 1
	v_lshl_add_u64 v[4:5], s[4:5], 0, v[154:155]
	s_lshl_b32 s16, s48, 1
	s_mov_b32 s17, s11
	v_lshl_add_u64 v[4:5], v[4:5], 0, s[16:17]
	v_lshlrev_b32_e32 v2, 4, v75
	v_lshl_add_u64 v[4:5], v[4:5], 0, v[2:3]
	s_and_b32 s53, s49, 31
	global_load_dwordx4 v[100:103], v[4:5], off
	global_load_dwordx4 v[104:107], v[4:5], off offset:32
	global_load_dwordx4 v[108:111], v[4:5], off offset:64
	global_load_dwordx4 v[112:115], v[4:5], off offset:96
	global_load_dwordx4 v[116:119], v[4:5], off offset:128
	global_load_dwordx4 v[120:123], v[4:5], off offset:160
	global_load_dwordx4 v[124:127], v[4:5], off offset:192
	global_load_dwordx4 v[128:131], v[4:5], off offset:224
	s_lshl_b32 s2, s53, 13
	s_add_u32 s0, s26, s2
	s_addc_u32 s1, s27, 0
	s_add_u32 s2, s28, s2
	v_lshlrev_b64 v[4:5], 2, v[156:157]
	s_addc_u32 s3, s29, 0
	v_lshl_add_u64 v[6:7], s[0:1], 0, v[4:5]
	v_lshl_add_u64 v[4:5], s[2:3], 0, v[4:5]
	global_load_dword v77, v[6:7], off
	global_load_dword v157, v[4:5], off
	s_lshl_b32 s70, s10, 10
	s_add_u32 s66, s24, s70
	s_addc_u32 s67, s25, 0
	s_add_u32 s66, s66, s16
	s_addc_u32 s67, s67, 0
	s_add_u32 s68, s30, s70
	s_addc_u32 s69, s31, 0
	s_add_u32 s68, s68, s16
	s_addc_u32 s69, s69, 0
	v_ashrrev_i32_e32 v228, 4, v74
	v_lshlrev_b32_e32 v230, 4, v74
	v_add_u32_e32 v232, s18, v228
	v_and_b32_e32 v230, 0xf0, v230
	v_mov_b32_e32 v231, 0
	v_ashrrev_i32_e32 v233, 31, v232
	v_lshl_add_u64 v[236:237], s[68:69], 0, v[230:231]
	v_lshl_add_u64 v[238:239], s[66:67], 0, v[230:231]
	v_lshlrev_b64 v[232:233], 10, v[232:233]
	v_lshl_add_u64 v[240:241], v[236:237], 0, v[232:233]
	v_lshl_add_u64 v[232:233], v[238:239], 0, v[232:233]
	global_load_dwordx4 v[200:203], v[240:241], off
	global_load_dwordx4 v[204:207], v[232:233], off
	v_add_u32_e32 v230, 0x200, v74
	v_ashrrev_i32_e32 v230, 4, v230
	v_add_u32_e32 v240, s18, v230
	v_ashrrev_i32_e32 v241, 31, v240
	v_lshlrev_b64 v[240:241], 10, v[240:241]
	v_lshl_add_u64 v[236:237], v[236:237], 0, v[240:241]
	v_lshl_add_u64 v[238:239], v[238:239], 0, v[240:241]
	global_load_dwordx4 v[208:211], v[236:237], off
	global_load_dwordx4 v[212:215], v[238:239], off
	s_lshl_b32 s71, s18, 2
	s_add_u32 s78, s0, s71
	s_addc_u32 s79, s1, 0
	global_load_dword v242, v3, s[78:79] offset:-4
	s_cmp_lg_u32 s50, 7
	s_mov_b64 s[20:21], -1
	s_barrier
	s_cbranch_scc0 .LBB0_2104
	v_cmp_gt_i32_e32 vcc, s51, v74
	v_lshl_add_u32 v78, v74, 2, 0
	s_and_saveexec_b64 s[20:21], vcc
	s_cbranch_execz .LBB0_2097
	s_mov_b32 s19, s11
	v_lshlrev_b32_e32 v4, 8, v74
	s_lshl_b64 s[22:23], s[18:19], 2
	s_add_u32 s54, s0, s22
	v_ashrrev_i32_e32 v5, 31, v4
	s_addc_u32 s55, s1, s23
	v_lshlrev_b64 v[4:5], 2, v[4:5]
	s_add_u32 s22, s2, s22
	v_lshl_add_u64 v[6:7], s[0:1], 0, v[4:5]
	v_lshl_add_u64 v[4:5], s[2:3], 0, v[4:5]
	s_addc_u32 s23, s3, s23
	global_load_dword v8, v3, s[54:55] offset:-4
	global_load_dword v10, v3, s[22:23] offset:-4
	global_load_dword v9, v[6:7], off offset:1020
	global_load_dword v11, v[4:5], off offset:1020
	v_lshl_add_u32 v4, s53, 3, v74
	v_ashrrev_i32_e32 v5, 31, v4
	v_lshl_add_u64 v[4:5], v[4:5], 2, s[6:7]
	global_load_dword v2, v[4:5], off
	s_waitcnt vmcnt(1)
	v_pk_add_f32 v[4:5], v[8:9], v[10:11]
	s_nop 0
	v_sub_f32_e32 v4, v4, v5
	s_waitcnt vmcnt(0)
	v_add_f32_e32 v2, v2, v4
	v_sub_f32_e32 v2, v2, v10
	v_mul_f32_e32 v2, 0x3fb8aa3b, v2
	v_exp_f32_e32 v2, v2
	ds_write_b32 v78, v2 offset:33024

; #define LAS __attribute__((address_space(3)))
; DI unsigned pk2(float lo, float hi) { f32x2 v = {lo, hi}; bf16x2_t b = __builtin_convertvector(v, bf16x2_t); return __builtin_bit_cast(unsigned, b); }
; DI int off128(int row, int ch) { return row * 256 + ((ch ^ swz128(row)) << 4); }
; DI void mlstm_unit(const Args& a, LAS unsigned char* lds, int b, int h, int J) {
;     ...
;             for (int i = 0; i < 8; ++i) { const int e = (tid + 512 * i) * 4, dk = e >> 7, dv = e & 127;
; #pragma unroll
;                 for (int j = 0; j < 4; ++j) *(LAS unsigned short*)(lds + M_CT + off128(dv + j, dk >> 3) + (dk & 7) * 2) = (unsigned short)(pk2(cacc[i][j], 0.f) & 0xffffu); }
;             if (tid < 128) NV[tid] = nacc;
;         }
;         __syncthreads();
.LBB0_2101:
	v_ashrrev_i32_e32 v5, 10, v36
	v_lshrrev_b32_e32 v4, 6, v36
	v_lshlrev_b32_e32 v7, 10, v74
	v_bitop3_b32 v8, v5, v74, 3 bitop3:0x78
	v_and_b32_e32 v4, 14, v4
	v_and_b32_e32 v7, 0x7c00, v7
	v_lshl_add_u32 v8, v8, 4, 0
	v_and_b32_e32 v2, 3, v74
	v_cvt_pk_bf16_f32 v6, v72, s0
	v_add3_u32 v8, v8, v7, v4
	ds_write_b16 v8, v6 offset:36864
	v_bitop3_b32 v8, v2, v5, 4 bitop3:0x36
	v_lshl_add_u32 v8, v8, 4, 0
	v_cvt_pk_bf16_f32 v6, v73, s0
	v_add3_u32 v8, v8, v7, v4
	ds_write_b16 v8, v6 offset:37120
	v_bitop3_b32 v8, v2, v5, 8 bitop3:0x36
	v_lshl_add_u32 v8, v8, 4, 0
	v_bitop3_b32 v5, v2, v5, 12 bitop3:0x36
	v_cvt_pk_bf16_f32 v6, v70, s0
	v_add3_u32 v8, v8, v7, v4
	v_lshl_add_u32 v5, v5, 4, 0
	ds_write_b16 v8, v6 offset:37376
	v_cvt_pk_bf16_f32 v6, v71, s0
	v_add3_u32 v5, v5, v7, v4
	ds_write_b16 v5, v6 offset:37632
	v_add_u32_e32 v5, 0x800, v36
	v_ashrrev_i32_e32 v5, 10, v5
	v_bitop3_b32 v8, v5, v74, 3 bitop3:0x78
	v_lshl_add_u32 v8, v8, 4, 0
	v_cvt_pk_bf16_f32 v6, v66, s0
	v_add3_u32 v8, v8, v7, v4
	ds_write_b16 v8, v6 offset:36864
	v_bitop3_b32 v8, v5, v2, 4 bitop3:0x1e
	v_lshl_add_u32 v8, v8, 4, 0
	v_cvt_pk_bf16_f32 v6, v67, s0
	v_add3_u32 v8, v8, v7, v4
	ds_write_b16 v8, v6 offset:37120
	v_bitop3_b32 v8, v5, v2, 8 bitop3:0x1e
	v_lshl_add_u32 v8, v8, 4, 0
	v_bitop3_b32 v5, v5, v2, 12 bitop3:0x1e
	v_cvt_pk_bf16_f32 v6, v62, s0
	v_add3_u32 v8, v8, v7, v4
	v_lshl_add_u32 v5, v5, 4, 0
	ds_write_b16 v8, v6 offset:37376
	v_cvt_pk_bf16_f32 v6, v63, s0
	v_add3_u32 v5, v5, v7, v4
	ds_write_b16 v5, v6 offset:37632
	v_add_u32_e32 v5, 0x1000, v36
	v_ashrrev_i32_e32 v5, 10, v5
	v_bitop3_b32 v8, v5, v74, 3 bitop3:0x78
	v_lshl_add_u32 v8, v8, 4, 0
	v_cvt_pk_bf16_f32 v6, v60, s0
	v_add3_u32 v8, v8, v7, v4
	ds_write_b16 v8, v6 offset:36864
	v_bitop3_b32 v8, v5, v2, 4 bitop3:0x1e
	v_lshl_add_u32 v8, v8, 4, 0
	v_cvt_pk_bf16_f32 v6, v61, s0
	v_add3_u32 v8, v8, v7, v4
	ds_write_b16 v8, v6 offset:37120
	v_bitop3_b32 v8, v5, v2, 8 bitop3:0x1e
	v_lshl_add_u32 v8, v8, 4, 0
	v_bitop3_b32 v5, v5, v2, 12 bitop3:0x1e
	v_cvt_pk_bf16_f32 v6, v58, s0
	v_add3_u32 v8, v8, v7, v4
	v_lshl_add_u32 v5, v5, 4, 0
	ds_write_b16 v8, v6 offset:37376
	v_cvt_pk_bf16_f32 v6, v59, s0
	v_add3_u32 v5, v5, v7, v4
	ds_write_b16 v5, v6 offset:37632
	v_add_u32_e32 v5, 0x1800, v36
	v_ashrrev_i32_e32 v5, 10, v5
	v_bitop3_b32 v8, v5, v74, 3 bitop3:0x78
	v_lshl_add_u32 v8, v8, 4, 0
	v_cvt_pk_bf16_f32 v6, v56, s0
	v_add3_u32 v8, v8, v7, v4
	ds_write_b16 v8, v6 offset:36864
	v_bitop3_b32 v8, v5, v2, 4 bitop3:0x1e
	v_lshl_add_u32 v8, v8, 4, 0
	v_cvt_pk_bf16_f32 v6, v57, s0
	v_add3_u32 v8, v8, v7, v4
	ds_write_b16 v8, v6 offset:37120
	v_bitop3_b32 v8, v5, v2, 8 bitop3:0x1e
	v_lshl_add_u32 v8, v8, 4, 0
	v_bitop3_b32 v5, v5, v2, 12 bitop3:0x1e
	v_cvt_pk_bf16_f32 v6, v54, s0
	v_add3_u32 v8, v8, v7, v4
	v_lshl_add_u32 v5, v5, 4, 0
	ds_write_b16 v8, v6 offset:37376
	v_cvt_pk_bf16_f32 v6, v55, s0
	v_add3_u32 v5, v5, v7, v4
	ds_write_b16 v5, v6 offset:37632
	v_add_u32_e32 v5, 0x2000, v36
	v_ashrrev_i32_e32 v5, 10, v5
	v_bitop3_b32 v8, v5, v74, 3 bitop3:0x78
	v_lshl_add_u32 v8, v8, 4, 0
	v_cvt_pk_bf16_f32 v6, v52, s0
	v_add3_u32 v8, v8, v7, v4
	ds_write_b16 v8, v6 offset:36864
	v_bitop3_b32 v8, v5, v2, 4 bitop3:0x1e
	v_lshl_add_u32 v8, v8, 4, 0
	v_cvt_pk_bf16_f32 v6, v53, s0
	v_add3_u32 v8, v8, v7, v4
	ds_write_b16 v8, v6 offset:37120
	v_bitop3_b32 v8, v5, v2, 8 bitop3:0x1e
	v_lshl_add_u32 v8, v8, 4, 0
	v_bitop3_b32 v5, v5, v2, 12 bitop3:0x1e
	v_cvt_pk_bf16_f32 v6, v50, s0
	v_add3_u32 v8, v8, v7, v4
	v_lshl_add_u32 v5, v5, 4, 0
	ds_write_b16 v8, v6 offset:37376
	v_cvt_pk_bf16_f32 v6, v51, s0
	v_add3_u32 v5, v5, v7, v4
	ds_write_b16 v5, v6 offset:37632
	v_add_u32_e32 v5, 0x2800, v36
	v_ashrrev_i32_e32 v5, 10, v5
	v_bitop3_b32 v8, v5, v74, 3 bitop3:0x78
	v_lshl_add_u32 v8, v8, 4, 0
	v_cvt_pk_bf16_f32 v6, v48, s0
	v_add3_u32 v8, v8, v7, v4
	ds_write_b16 v8, v6 offset:36864
	v_bitop3_b32 v8, v5, v2, 4 bitop3:0x1e
	v_lshl_add_u32 v8, v8, 4, 0
	v_cvt_pk_bf16_f32 v6, v49, s0
	v_add3_u32 v8, v8, v7, v4
	ds_write_b16 v8, v6 offset:37120
	v_bitop3_b32 v8, v5, v2, 8 bitop3:0x1e
	v_lshl_add_u32 v8, v8, 4, 0
	v_bitop3_b32 v5, v5, v2, 12 bitop3:0x1e
	v_cvt_pk_bf16_f32 v6, v46, s0
	v_add3_u32 v8, v8, v7, v4
	v_lshl_add_u32 v5, v5, 4, 0
	ds_write_b16 v8, v6 offset:37376
	v_cvt_pk_bf16_f32 v6, v47, s0
	v_add3_u32 v5, v5, v7, v4
	ds_write_b16 v5, v6 offset:37632
	v_add_u32_e32 v5, 0x3000, v36
	v_ashrrev_i32_e32 v5, 10, v5
	v_bitop3_b32 v8, v5, v74, 3 bitop3:0x78
	v_lshl_add_u32 v8, v8, 4, 0
	v_cvt_pk_bf16_f32 v6, v44, s0
	v_add3_u32 v8, v8, v7, v4
	ds_write_b16 v8, v6 offset:36864
	v_bitop3_b32 v8, v5, v2, 4 bitop3:0x1e
	v_lshl_add_u32 v8, v8, 4, 0
	v_cvt_pk_bf16_f32 v6, v45, s0
	v_add3_u32 v8, v8, v7, v4
	ds_write_b16 v8, v6 offset:37120
	v_bitop3_b32 v8, v5, v2, 8 bitop3:0x1e
	v_lshl_add_u32 v8, v8, 4, 0
	v_bitop3_b32 v5, v5, v2, 12 bitop3:0x1e
	v_cvt_pk_bf16_f32 v6, v42, s0
	v_add3_u32 v8, v8, v7, v4
	v_lshl_add_u32 v5, v5, 4, 0
	ds_write_b16 v8, v6 offset:37376
	v_cvt_pk_bf16_f32 v6, v43, s0
	v_add3_u32 v5, v5, v7, v4
	ds_write_b16 v5, v6 offset:37632
	v_add_u32_e32 v5, 0x3800, v36
	v_ashrrev_i32_e32 v5, 10, v5
	v_bitop3_b32 v8, v5, v74, 3 bitop3:0x78
	v_lshl_add_u32 v8, v8, 4, 0
	v_cvt_pk_bf16_f32 v6, v40, s0
	v_add3_u32 v8, v8, v7, v4
	ds_write_b16 v8, v6 offset:36864
	v_bitop3_b32 v8, v5, v2, 4 bitop3:0x1e
	v_lshl_add_u32 v8, v8, 4, 0
	v_cvt_pk_bf16_f32 v6, v41, s0
	v_add3_u32 v8, v8, v7, v4
	ds_write_b16 v8, v6 offset:37120
	v_bitop3_b32 v8, v5, v2, 8 bitop3:0x1e
	v_lshl_add_u32 v8, v8, 4, 0
	v_bitop3_b32 v2, v5, v2, 12 bitop3:0x1e
	v_cvt_pk_bf16_f32 v6, v38, s0
	v_add3_u32 v8, v8, v7, v4
	v_lshl_add_u32 v2, v2, 4, 0
	ds_write_b16 v8, v6 offset:37376
	v_cvt_pk_bf16_f32 v6, v39, s0
	v_add3_u32 v2, v2, v7, v4
	ds_write_b16 v2, v6 offset:37632
	s_and_saveexec_b64 s[20:21], s[2:3]
	ds_write_b32 v78, v37 offset:33280
	s_or_b64 exec, exec, s[20:21]
	v_lshlrev_b32_e32 v2, 2, v76
	v_and_b32_e32 v2, 12, v2
	v_bfe_u32 v68, v74, 2, 2
	v_lshl_add_u32 v28, v76, 8, 0
	v_bitop3_b32 v4, v2, v75, v68 bitop3:0x36
	v_lshl_add_u32 v64, v4, 4, v28
	s_waitcnt lgkmcnt(0)
	s_barrier
; #define LAS __attribute__((address_space(3)))
; DI int off128(int row, int ch) { return row * 256 + ((ch ^ swz128(row)) << 4); }
; #define MFMA32(a, b, c) __builtin_amdgcn_mfma_f32_32x32x16_bf16((a), (b), (c), 0, 0, 0)
; DI void mlstm_unit(const Args& a, LAS unsigned char* lds, int b, int h, int J) {
;     ...
;         __syncthreads();
; #pragma unroll
;         for (int db = 0; db < 4; ++db)
; #pragma unroll
;             for (int ks = 0; ks < 8; ++ks) { const bf16x8 cf = *(const LAS bf16x8*)(lds + M_CT + off128(32 * db + r, 2 * ks + h2)); O[db] = MFMA32(cf, qf[ks], O[db]); }
;         const float sc = __expf(aln - ALPHA[e1]);
; #pragma unroll
;         for (int db = 0; db < 4; ++db)
; #pragma unroll
;             for (int reg = 0; reg < 16; ++reg) O[db][reg] *= sc;
	ds_read_b128 v[4:7], v64 offset:36864
	ds_read_b128 v[20:23], v64 offset:45056
	v_or_b32_e32 v8, 2, v75
	v_bitop3_b32 v24, v2, v8, v68 bitop3:0x36
	v_lshl_add_u32 v65, v24, 4, v28
	ds_read_b128 v[24:27], v65 offset:36864
	ds_read_b128 v[36:39], v65 offset:45056
	s_waitcnt lgkmcnt(3)
	v_mfma_f32_32x32x16_bf16 v[4:19], v[4:7], v[100:103], 0
	v_or_b32_e32 v29, 4, v75
	v_bitop3_b32 v29, v2, v29, v68 bitop3:0x36
	v_lshl_add_u32 v66, v29, 4, v28
	v_or_b32_e32 v29, 6, v75
	v_bitop3_b32 v29, v2, v29, v68 bitop3:0x36
	v_lshl_add_u32 v67, v29, 4, v28
	ds_read_b128 v[40:43], v66 offset:45056
	s_waitcnt lgkmcnt(2)
	v_mfma_f32_32x32x16_bf16 v[4:19], v[24:27], v[104:107], v[4:19]
	ds_read_b128 v[24:27], v66 offset:36864
	v_or_b32_e32 v29, 8, v75
	v_bitop3_b32 v29, v2, v29, v68 bitop3:0x36
	v_lshl_add_u32 v69, v29, 4, v28
	ds_read_b128 v[44:47], v67 offset:45056
	v_or_b32_e32 v29, 10, v75
	v_bitop3_b32 v29, v2, v29, v68 bitop3:0x36
	s_waitcnt lgkmcnt(1)
	v_mfma_f32_32x32x16_bf16 v[4:19], v[24:27], v[108:111], v[4:19]
	ds_read_b128 v[24:27], v67 offset:36864
	v_lshl_add_u32 v90, v29, 4, v28
	ds_read_b128 v[48:51], v69 offset:45056
	v_or_b32_e32 v29, 12, v75
	v_bitop3_b32 v29, v2, v29, v68 bitop3:0x36
	v_lshl_add_u32 v94, v29, 4, v28
	v_or_b32_e32 v29, 14, v75
	s_waitcnt lgkmcnt(1)
	v_mfma_f32_32x32x16_bf16 v[4:19], v[24:27], v[112:115], v[4:19]
	ds_read_b128 v[24:27], v69 offset:36864
	ds_read_b128 v[52:55], v90 offset:45056
	v_bitop3_b32 v2, v2, v29, v68 bitop3:0x36
	v_lshl_add_u32 v2, v2, 4, v28
	s_mov_b32 s19, s11
	s_lshl_b64 s[2:3], s[18:19], 2
	s_add_u32 s0, s0, s2
	s_waitcnt lgkmcnt(1)
	v_mfma_f32_32x32x16_bf16 v[4:19], v[24:27], v[116:119], v[4:19]
	ds_read_b128 v[24:27], v90 offset:36864
	ds_read_b128 v[56:59], v94 offset:45056
	s_addc_u32 s1, s1, s3
	s_mov_b64 s[20:21], 0
	s_waitcnt lgkmcnt(1)
	v_mfma_f32_32x32x16_bf16 v[4:19], v[24:27], v[120:123], v[4:19]
	ds_read_b128 v[24:27], v94 offset:36864
	s_waitcnt lgkmcnt(0)
	v_mfma_f32_32x32x16_bf16 v[4:19], v[24:27], v[124:127], v[4:19]
	ds_read_b128 v[24:27], v2 offset:36864
	ds_read_b128 v[60:63], v2 offset:45056
	s_waitcnt lgkmcnt(1)
	v_mfma_f32_32x32x16_bf16 v[4:19], v[24:27], v[128:131], v[4:19]
	v_mfma_f32_32x32x16_bf16 v[20:35], v[20:23], v[100:103], 0
	v_mfma_f32_32x32x16_bf16 v[20:35], v[36:39], v[104:107], v[20:35]
	v_mfma_f32_32x32x16_bf16 v[20:35], v[40:43], v[108:111], v[20:35]
	v_mfma_f32_32x32x16_bf16 v[20:35], v[44:47], v[112:115], v[20:35]
	v_mfma_f32_32x32x16_bf16 v[20:35], v[48:51], v[116:119], v[20:35]
	v_mfma_f32_32x32x16_bf16 v[20:35], v[52:55], v[120:123], v[20:35]
	ds_read_b128 v[36:39], v64 offset:53248
	ds_read_b128 v[52:55], v64 offset:61440
	s_waitcnt lgkmcnt(1)
	v_mfma_f32_32x32x16_bf16 v[36:51], v[36:39], v[100:103], 0
	v_mfma_f32_32x32x16_bf16 v[20:35], v[56:59], v[124:127], v[20:35]
	ds_read_b128 v[56:59], v65 offset:53248
	ds_read_b128 v[70:73], v65 offset:61440
	s_waitcnt lgkmcnt(1)
	v_mfma_f32_32x32x16_bf16 v[36:51], v[56:59], v[104:107], v[36:51]
	ds_read_b128 v[56:59], v66 offset:53248
	ds_read_b128 v[78:81], v66 offset:61440
	s_waitcnt lgkmcnt(1)
	v_mfma_f32_32x32x16_bf16 v[36:51], v[56:59], v[108:111], v[36:51]
	ds_read_b128 v[56:59], v67 offset:53248
	ds_read_b128 v[82:85], v67 offset:61440
	s_waitcnt lgkmcnt(1)
	v_mfma_f32_32x32x16_bf16 v[36:51], v[56:59], v[112:115], v[36:51]
	ds_read_b128 v[56:59], v69 offset:53248
	ds_read_b128 v[86:89], v69 offset:61440
	v_lshl_add_u32 v69, v75, 5, 0
	s_waitcnt lgkmcnt(1)
	v_mfma_f32_32x32x16_bf16 v[36:51], v[56:59], v[116:119], v[36:51]
	ds_read_b128 v[56:59], v90 offset:53248
	ds_read_b128 v[90:93], v90 offset:61440
	s_waitcnt lgkmcnt(1)
	v_mfma_f32_32x32x16_bf16 v[36:51], v[56:59], v[120:123], v[36:51]
	ds_read_b128 v[56:59], v94 offset:53248
	ds_read_b128 v[94:97], v94 offset:61440
	s_waitcnt lgkmcnt(1)
	v_mfma_f32_32x32x16_bf16 v[36:51], v[56:59], v[124:127], v[36:51]
	ds_read_b128 v[56:59], v2 offset:53248
	ds_read_b128 v[132:135], v2 offset:61440
	v_mov_b32_e32 v2, v242
	s_waitcnt vmcnt(0)
	v_sub_f32_e32 v2, v77, v2
	v_mfma_f32_32x32x16_bf16 v[20:35], v[60:63], v[128:131], v[20:35]
	v_mul_f32_e32 v2, 0x3fb8aa3b, v2
	v_exp_f32_e32 v2, v2
	s_nop 0
	v_pk_mul_f32 v[18:19], v[18:19], v[2:3] op_sel_hi:[1,0]
	v_pk_mul_f32 v[16:17], v[16:17], v[2:3] op_sel_hi:[1,0]
	s_waitcnt lgkmcnt(1)
	v_mfma_f32_32x32x16_bf16 v[36:51], v[56:59], v[128:131], v[36:51]
	v_mul_f32_e64 v14, v14, v2
	v_mul_f32_e64 v15, v15, v2
	v_mul_f32_e64 v12, v12, v2
	v_mul_f32_e64 v13, v13, v2
	v_mul_f32_e64 v10, v10, v2
	v_mul_f32_e64 v11, v11, v2
	v_pk_mul_f32 v[8:9], v[8:9], v[2:3] op_sel_hi:[1,0]
	v_pk_mul_f32 v[6:7], v[6:7], v[2:3] op_sel_hi:[1,0]
	v_pk_mul_f32 v[4:5], v[4:5], v[2:3] op_sel_hi:[1,0]
	v_pk_mul_f32 v[34:35], v[34:35], v[2:3] op_sel_hi:[1,0]
	v_mfma_f32_32x32x16_bf16 v[52:67], v[52:55], v[100:103], 0
	v_mul_f32_e64 v32, v32, v2
	v_mul_f32_e64 v33, v33, v2
	v_mul_f32_e64 v30, v30, v2
	v_mul_f32_e64 v31, v31, v2
	v_mul_f32_e64 v28, v28, v2
	v_mul_f32_e64 v29, v29, v2
	v_pk_mul_f32 v[26:27], v[26:27], v[2:3] op_sel_hi:[1,0]
	v_pk_mul_f32 v[24:25], v[24:25], v[2:3] op_sel_hi:[1,0]
	v_pk_mul_f32 v[22:23], v[22:23], v[2:3] op_sel_hi:[1,0]
	v_pk_mul_f32 v[20:21], v[20:21], v[2:3] op_sel_hi:[1,0]
	v_mfma_f32_32x32x16_bf16 v[52:67], v[70:73], v[104:107], v[52:67]
	v_mul_f32_e64 v50, v50, v2
	v_mul_f32_e64 v51, v51, v2
	v_mul_f32_e64 v48, v48, v2
	v_mul_f32_e64 v49, v49, v2
	v_mul_f32_e64 v46, v46, v2
	v_mul_f32_e64 v47, v47, v2
	v_pk_mul_f32 v[44:45], v[44:45], v[2:3] op_sel_hi:[1,0]
	v_pk_mul_f32 v[42:43], v[42:43], v[2:3] op_sel_hi:[1,0]
	v_pk_mul_f32 v[40:41], v[40:41], v[2:3] op_sel_hi:[1,0]
	v_pk_mul_f32 v[38:39], v[38:39], v[2:3] op_sel_hi:[1,0]
	v_mfma_f32_32x32x16_bf16 v[52:67], v[78:81], v[108:111], v[52:67]
	v_mul_f32_e64 v36, v36, v2
	v_mul_f32_e64 v37, v37, v2
	v_mfma_f32_32x32x16_bf16 v[52:67], v[82:85], v[112:115], v[52:67]
	v_mfma_f32_32x32x16_bf16 v[52:67], v[86:89], v[116:119], v[52:67]
	ds_read_b128 v[70:73], v69 offset:33280
	ds_read_b128 v[78:81], v69 offset:33296
	ds_read_b128 v[82:85], v69 offset:33344
	ds_read_b128 v[86:89], v69 offset:33360
	v_mfma_f32_32x32x16_bf16 v[52:67], v[90:93], v[120:123], v[52:67]
	s_waitcnt lgkmcnt(1)
; #define LAS __attribute__((address_space(3)))
; DI void mlstm_unit(const Args& a, LAS unsigned char* lds, int b, int h, int J) {
;     ...
;         float qn = 0.f;
; #pragma unroll
;         for (int ks = 0; ks < 8; ++ks) { const u32x4 qw = __builtin_bit_cast(u32x4, qf[ks]); const f32x4 n0 = *(const LAS f32x4*)(NV + 16 * ks + 8 * h2), n1 = *(const LAS f32x4*)(NV + 16 * ks + 8 * h2 + 4);
;             qn += bf2f(qw.x & 0xffffu) * n0.x + bf2f(qw.x >> 16) * n0.y + bf2f(qw.y & 0xffffu) * n0.z + bf2f(qw.y >> 16) * n0.w + bf2f(qw.z & 0xffffu) * n1.x + bf2f(qw.z >> 16) * n1.y + bf2f(qw.w & 0xffffu) * n1.z + bf2f(qw.w >> 16) * n1.w; }
;         den = sc * qn;
	v_mov_b32_e32 v93, v82
	v_mov_b32_e32 v82, v71
	v_lshlrev_b32_e32 v91, 16, v104
	v_lshlrev_b32_e32 v90, 16, v100
	v_mov_b32_e32 v92, v70
	v_mfma_f32_32x32x16_bf16 v[52:67], v[94:97], v[124:127], v[52:67]
	v_and_b32_e32 v95, 0xffff0000, v104
	v_and_b32_e32 v94, 0xffff0000, v100
	v_mul_f32_e64 v70, v82, v94
	v_mul_f32_e64 v71, v83, v95
	v_lshlrev_b32_e32 v83, 16, v105
	v_pk_fma_f32 v[70:71], v[92:93], v[90:91], v[70:71]
	v_lshlrev_b32_e32 v82, 16, v101
	v_mov_b32_e32 v90, v72
	v_mov_b32_e32 v91, v84
	v_pk_fma_f32 v[70:71], v[90:91], v[82:83], v[70:71]
	v_and_b32_e32 v83, 0xffff0000, v105
	v_and_b32_e32 v82, 0xffff0000, v101
	v_mov_b32_e32 v84, v73
	v_pk_fma_f32 v[70:71], v[84:85], v[82:83], v[70:71]
	v_lshlrev_b32_e32 v73, 16, v106
	v_lshlrev_b32_e32 v72, 16, v102
	v_mov_b32_e32 v82, v78
	s_waitcnt lgkmcnt(0)
	v_mov_b32_e32 v83, v86
	v_pk_fma_f32 v[70:71], v[82:83], v[72:73], v[70:71]
	v_and_b32_e32 v73, 0xffff0000, v106
	v_and_b32_e32 v72, 0xffff0000, v102
	v_mov_b32_e32 v86, v79
	v_pk_fma_f32 v[70:71], v[86:87], v[72:73], v[70:71]
	v_lshlrev_b32_e32 v73, 16, v107
	v_lshlrev_b32_e32 v72, 16, v103
	v_mov_b32_e32 v78, v80
	v_mov_b32_e32 v79, v88
	v_pk_fma_f32 v[70:71], v[78:79], v[72:73], v[70:71]
	v_and_b32_e32 v73, 0xffff0000, v107
	v_and_b32_e32 v72, 0xffff0000, v103
	v_mov_b32_e32 v88, v81
	v_pk_fma_f32 v[70:71], v[88:89], v[72:73], v[70:71]
	v_and_b32_e32 v95, 0xffff0000, v112
	v_add_f32_e32 v70, 0, v70
	v_add_f32_e32 v96, v70, v71
	ds_read_b128 v[70:73], v69 offset:33408
	ds_read_b128 v[78:81], v69 offset:33424
	ds_read_b128 v[82:85], v69 offset:33472
	ds_read_b128 v[86:89], v69 offset:33488
	v_and_b32_e32 v94, 0xffff0000, v108
	v_lshlrev_b32_e32 v91, 16, v112
	v_lshlrev_b32_e32 v90, 16, v108
	s_waitcnt lgkmcnt(1)
	v_mov_b32_e32 v93, v82
	v_mov_b32_e32 v82, v71
	v_mov_b32_e32 v92, v70
	v_pk_mul_f32 v[70:71], v[82:83], v[94:95]
	v_lshlrev_b32_e32 v83, 16, v113
	v_pk_fma_f32 v[70:71], v[92:93], v[90:91], v[70:71]
	v_lshlrev_b32_e32 v82, 16, v109
	v_mov_b32_e32 v90, v72
	v_mov_b32_e32 v91, v84
	v_pk_fma_f32 v[70:71], v[90:91], v[82:83], v[70:71]
	v_and_b32_e32 v83, 0xffff0000, v113
	v_and_b32_e32 v82, 0xffff0000, v109
	v_mov_b32_e32 v84, v73
	v_pk_fma_f32 v[70:71], v[84:85], v[82:83], v[70:71]
	v_lshlrev_b32_e32 v73, 16, v114
	v_lshlrev_b32_e32 v72, 16, v110
	v_mov_b32_e32 v82, v78
	s_waitcnt lgkmcnt(0)
	v_mov_b32_e32 v83, v86
	v_pk_fma_f32 v[70:71], v[82:83], v[72:73], v[70:71]
	v_and_b32_e32 v73, 0xffff0000, v114
	v_and_b32_e32 v72, 0xffff0000, v110
	v_mov_b32_e32 v86, v79
	v_pk_fma_f32 v[70:71], v[86:87], v[72:73], v[70:71]
	v_lshlrev_b32_e32 v73, 16, v115
	v_lshlrev_b32_e32 v72, 16, v111
	v_mov_b32_e32 v78, v80
	v_mov_b32_e32 v79, v88
	v_pk_fma_f32 v[70:71], v[78:79], v[72:73], v[70:71]
	v_and_b32_e32 v73, 0xffff0000, v115
	v_and_b32_e32 v72, 0xffff0000, v111
	v_mov_b32_e32 v88, v81
	v_pk_fma_f32 v[70:71], v[88:89], v[72:73], v[70:71]
	v_and_b32_e32 v95, 0xffff0000, v120
	v_add_f32_e32 v70, v96, v70
	v_add_f32_e32 v96, v70, v71
	ds_read_b128 v[70:73], v69 offset:33536
	ds_read_b128 v[78:81], v69 offset:33552
	ds_read_b128 v[82:85], v69 offset:33600
	ds_read_b128 v[86:89], v69 offset:33616
	v_and_b32_e32 v94, 0xffff0000, v116
	v_lshlrev_b32_e32 v91, 16, v120
	v_lshlrev_b32_e32 v90, 16, v116
	s_waitcnt lgkmcnt(1)
	v_mov_b32_e32 v93, v82
	v_mov_b32_e32 v82, v71
	v_mov_b32_e32 v92, v70
	v_pk_mul_f32 v[70:71], v[82:83], v[94:95]
	v_lshlrev_b32_e32 v83, 16, v121
	v_pk_fma_f32 v[70:71], v[92:93], v[90:91], v[70:71]
	v_lshlrev_b32_e32 v82, 16, v117
	v_mov_b32_e32 v90, v72
	v_mov_b32_e32 v91, v84
	v_pk_fma_f32 v[70:71], v[90:91], v[82:83], v[70:71]
	v_and_b32_e32 v83, 0xffff0000, v121
	v_and_b32_e32 v82, 0xffff0000, v117
	v_mov_b32_e32 v84, v73
	v_pk_fma_f32 v[70:71], v[84:85], v[82:83], v[70:71]
	v_lshlrev_b32_e32 v73, 16, v122
	v_lshlrev_b32_e32 v72, 16, v118
	v_mov_b32_e32 v82, v78
	s_waitcnt lgkmcnt(0)
	v_mov_b32_e32 v83, v86
	v_pk_fma_f32 v[70:71], v[82:83], v[72:73], v[70:71]
	v_and_b32_e32 v73, 0xffff0000, v122
	v_and_b32_e32 v72, 0xffff0000, v118
	v_mov_b32_e32 v86, v79
	v_pk_fma_f32 v[70:71], v[86:87], v[72:73], v[70:71]
	v_lshlrev_b32_e32 v73, 16, v123
	v_lshlrev_b32_e32 v72, 16, v119
	v_mov_b32_e32 v78, v80
	v_mov_b32_e32 v79, v88
	v_pk_fma_f32 v[70:71], v[78:79], v[72:73], v[70:71]
	v_and_b32_e32 v73, 0xffff0000, v123
	v_and_b32_e32 v72, 0xffff0000, v119
	v_mov_b32_e32 v88, v81
	v_pk_fma_f32 v[70:71], v[88:89], v[72:73], v[70:71]
	v_and_b32_e32 v95, 0xffff0000, v128
	v_add_f32_e32 v70, v96, v70
	v_add_f32_e32 v96, v70, v71
	ds_read_b128 v[70:73], v69 offset:33664
	ds_read_b128 v[78:81], v69 offset:33680
	ds_read_b128 v[82:85], v69 offset:33728
	ds_read_b128 v[86:89], v69 offset:33744
	v_and_b32_e32 v94, 0xffff0000, v124
	v_lshlrev_b32_e32 v91, 16, v128
	v_lshlrev_b32_e32 v90, 16, v124
	s_waitcnt lgkmcnt(1)
	v_mov_b32_e32 v93, v82
	v_mov_b32_e32 v82, v71
	v_mov_b32_e32 v92, v70
	v_pk_mul_f32 v[70:71], v[82:83], v[94:95]
	v_lshlrev_b32_e32 v83, 16, v129
	v_pk_fma_f32 v[70:71], v[92:93], v[90:91], v[70:71]
	v_lshlrev_b32_e32 v82, 16, v125
	v_mov_b32_e32 v90, v72
	v_mov_b32_e32 v91, v84
	v_mfma_f32_32x32x16_bf16 v[52:67], v[132:135], v[128:131], v[52:67]
	v_fma_f32 v70, v90, v82, v70
	v_fma_f32 v71, v91, v83, v71
	v_and_b32_e32 v83, 0xffff0000, v129
	v_and_b32_e32 v82, 0xffff0000, v125
	v_mov_b32_e32 v84, v73
	v_pk_fma_f32 v[70:71], v[84:85], v[82:83], v[70:71]
	v_lshlrev_b32_e32 v73, 16, v130
	v_lshlrev_b32_e32 v72, 16, v126
	v_mov_b32_e32 v82, v78
	s_waitcnt lgkmcnt(0)
	v_mov_b32_e32 v83, v86
	v_pk_fma_f32 v[70:71], v[82:83], v[72:73], v[70:71]
	v_and_b32_e32 v73, 0xffff0000, v130
	v_and_b32_e32 v72, 0xffff0000, v126
	v_mov_b32_e32 v86, v79
	v_pk_fma_f32 v[70:71], v[86:87], v[72:73], v[70:71]
	v_lshlrev_b32_e32 v73, 16, v131
	v_lshlrev_b32_e32 v72, 16, v127
	v_mov_b32_e32 v78, v80
	v_mov_b32_e32 v79, v88
	v_pk_fma_f32 v[70:71], v[78:79], v[72:73], v[70:71]
	v_and_b32_e32 v73, 0xffff0000, v131
	v_and_b32_e32 v72, 0xffff0000, v127
	v_mov_b32_e32 v88, v81
	v_pk_fma_f32 v[70:71], v[88:89], v[72:73], v[70:71]
	v_pk_mul_f32 v[66:67], v[66:67], v[2:3] op_sel_hi:[1,0]
	v_add_f32_e32 v69, v96, v70
	v_add_f32_e32 v69, v69, v71
	v_pk_mul_f32 v[64:65], v[64:65], v[2:3] op_sel_hi:[1,0]
	v_pk_mul_f32 v[62:63], v[62:63], v[2:3] op_sel_hi:[1,0]
	v_pk_mul_f32 v[60:61], v[60:61], v[2:3] op_sel_hi:[1,0]
	v_pk_mul_f32 v[58:59], v[58:59], v[2:3] op_sel_hi:[1,0]
	v_pk_mul_f32 v[56:57], v[56:57], v[2:3] op_sel_hi:[1,0]
	v_pk_mul_f32 v[54:55], v[54:55], v[2:3] op_sel_hi:[1,0]
	v_pk_mul_f32 v[52:53], v[52:53], v[2:3] op_sel_hi:[1,0]
	v_mul_f32_e32 v167, v2, v69
